# add P3 final-epilogue S2 load hoist (16 loads up front, counted vmcnt)
# speedup vs baseline: 1.0161x; 1.0006x over previous
; __device__ __forceinline__ float bf_lo(unsigned w) { return __uint_as_float(w << 16); }
; __device__ __forceinline__ float bf_hi(unsigned w) { return __uint_as_float(w & 0xffff0000u); }
; __device__ __forceinline__ u32x4 pack8(f32x4 v0, f32x4 v1) { u32x4 w; w.x = cvt_pk_bf16(v0[0], v0[1]); w.y = cvt_pk_bf16(v0[2], v0[3]); w.z = cvt_pk_bf16(v1[0], v1[1]); w.w = cvt_pk_bf16(v1[2], v1[3]); return w; }
;     __device__ __forceinline__ void operator()(const Acc& acc, const Unit& u, int wr, int wc, int fr, int fq) const {
;         const size_t o0 = (size_t)(u.pm * 256 + wr * 64 + fr) * DM + u.pn * 256 + wc * 32 + 8 * fq;
; #pragma unroll
;         for (int ai = 0; ai < 2; ++ai)
; #pragma unroll
;             for (int m = 0; m < 4; ++m)
; #pragma unroll
;                 for (int bj = 0; bj < 2; ++bj) { const size_t o = o0 + (size_t)(ai * 128 + m * 16) * DM + bj * 128; const u32x4 w = __builtin_nontemporal_load((const u32x4*)(S2 + o));
;                     const f32x4 v0 = acc[ai][bj][m][0] * (f32x4){bf_lo(w.x), bf_hi(w.x), bf_lo(w.y), bf_hi(w.y)}, v1 = acc[ai][bj][m][1] * (f32x4){bf_lo(w.z), bf_hi(w.z), bf_lo(w.w), bf_hi(w.w)};
;                     *(u32x4*)(MG + o) = pack8(v0, v1); }
.LBB0_668:
	s_cmp_lg_u32 s25, 0
	s_cselect_b64 s[22:23], -1, 0
	v_lshl_add_u32 v128, s24, 8, v175
	v_ashrrev_i32_e32 v129, 31, v128
	s_and_b64 vcc, exec, s[22:23]
	s_cbranch_vccz .LBB0_676
	s_lshl_b32 s15, s50, 8
	s_ashr_i32 s17, s15, 31
	v_lshlrev_b64 v[130:131], 11, v[128:129]
	v_mov_b32_e32 v133, s17
	v_or_b32_e32 v132, s15, v174
	v_lshl_add_u64 v[130:131], v[130:131], 0, v[132:133]
	v_readlane_b32 s24, v248, 50
	v_lshlrev_b64 v[142:143], 1, v[130:131]
	v_readlane_b32 s25, v248, 51
	v_lshl_add_u64 v[130:131], s[4:5], 0, v[142:143]
	s_nop 0
	v_lshl_add_u64 v[132:133], s[24:25], 0, v[142:143]
	global_load_dwordx4 v[134:137], v[132:133], off nt
	global_load_dwordx4 v[202:205], v[132:133], off offset:256 nt
	v_add_co_u32_e32 v250, vcc, s37, v132
	s_nop 1
	v_addc_co_u32_e32 v251, vcc, 0, v133, vcc
	global_load_dwordx4 v[206:209], v[250:251], off nt
	global_load_dwordx4 v[210:213], v[250:251], off offset:256 nt
	v_add_co_u32_e32 v250, vcc, s42, v132
	s_nop 1
	v_addc_co_u32_e32 v251, vcc, 0, v133, vcc
	global_load_dwordx4 v[214:217], v[250:251], off nt
	global_load_dwordx4 v[218:221], v[250:251], off offset:256 nt
	v_add_co_u32_e32 v250, vcc, s43, v132
	s_nop 1
	v_addc_co_u32_e32 v251, vcc, 0, v133, vcc
	global_load_dwordx4 v[222:225], v[250:251], off nt
	global_load_dwordx4 v[226:229], v[250:251], off offset:256 nt
	v_add_co_u32_e32 v250, vcc, s44, v132
	s_nop 1
	v_addc_co_u32_e32 v251, vcc, 0, v133, vcc
	global_load_dwordx4 v[230:233], v[250:251], off nt
	global_load_dwordx4 v[234:237], v[250:251], off offset:256 nt
	v_add_co_u32_e32 v250, vcc, s45, v132
	s_nop 1
	v_addc_co_u32_e32 v251, vcc, 0, v133, vcc
	global_load_dwordx4 v[238:241], v[250:251], off nt
	global_load_dwordx4 v[242:245], v[250:251], off offset:256 nt
	v_add_co_u32_e32 v250, vcc, s46, v132
	s_nop 1
	v_addc_co_u32_e32 v251, vcc, 0, v133, vcc
	global_load_dwordx4 v[164:167], v[250:251], off nt
	global_load_dwordx4 v[168:171], v[250:251], off offset:256 nt
	v_add_co_u32_e32 v250, vcc, s47, v132
	s_nop 1
	v_addc_co_u32_e32 v251, vcc, 0, v133, vcc
	global_load_dwordx4 v[176:179], v[250:251], off nt
	global_load_dwordx4 v[180:183], v[250:251], off offset:256 nt
	v_or_b32_e32 v142, 0x100, v142
	v_lshl_add_u64 v[138:139], s[24:25], 0, v[142:143]
	v_lshl_add_u64 v[142:143], s[4:5], 0, v[142:143]
	s_waitcnt vmcnt(15)
	v_lshlrev_b32_e32 v140, 16, v134
	v_and_b32_e32 v141, 0xffff0000, v134
	v_lshlrev_b32_e32 v134, 16, v135
	v_and_b32_e32 v135, 0xffff0000, v135
	v_lshlrev_b32_e32 v144, 16, v136
	v_and_b32_e32 v145, 0xffff0000, v136
	v_lshlrev_b32_e32 v136, 16, v137
	v_and_b32_e32 v137, 0xffff0000, v137
	v_pk_mul_f32 v[146:147], v[126:127], v[134:135]
	v_pk_mul_f32 v[134:135], v[124:125], v[140:141]
	v_pk_mul_f32 v[140:141], v[122:123], v[136:137]
	v_pk_mul_f32 v[136:137], v[120:121], v[144:145]
	v_cvt_pk_bf16_f32 v134, v134, v135
	v_cvt_pk_bf16_f32 v135, v146, v147
	v_add_co_u32_e32 v144, vcc, s37, v132
	v_cvt_pk_bf16_f32 v136, v136, v137
	v_cvt_pk_bf16_f32 v137, v140, v141
	s_nop 0
	v_addc_co_u32_e32 v145, vcc, 0, v133, vcc
	global_store_dwordx4 v[130:131], v[134:137], off
	s_waitcnt vmcnt(15)
	v_mov_b32_e32 v138, v202
	v_mov_b32_e32 v139, v203
	v_mov_b32_e32 v140, v204
	v_mov_b32_e32 v141, v205
	s_nop 0
	v_lshlrev_b32_e32 v134, 16, v138
	v_and_b32_e32 v135, 0xffff0000, v138
	v_lshlrev_b32_e32 v136, 16, v139
	v_and_b32_e32 v137, 0xffff0000, v139
	v_lshlrev_b32_e32 v138, 16, v140
	v_and_b32_e32 v139, 0xffff0000, v140
	v_lshlrev_b32_e32 v140, 16, v141
	v_and_b32_e32 v141, 0xffff0000, v141
	v_pk_mul_f32 v[136:137], v[94:95], v[136:137]
	v_pk_mul_f32 v[134:135], v[92:93], v[134:135]
	v_pk_mul_f32 v[140:141], v[90:91], v[140:141]
	v_pk_mul_f32 v[138:139], v[88:89], v[138:139]
	v_cvt_pk_bf16_f32 v134, v134, v135
	v_cvt_pk_bf16_f32 v135, v136, v137
	s_nop 0
	v_cvt_pk_bf16_f32 v136, v138, v139
	v_cvt_pk_bf16_f32 v137, v140, v141
	s_nop 0
	global_store_dwordx4 v[142:143], v[134:137], off
	v_add_co_u32_e32 v142, vcc, s37, v130
	s_waitcnt vmcnt(15)
	v_mov_b32_e32 v138, v206
	v_mov_b32_e32 v139, v207
	v_mov_b32_e32 v140, v208
	v_mov_b32_e32 v141, v209
	v_lshlrev_b32_e32 v134, 16, v138
	v_and_b32_e32 v135, 0xffff0000, v138
	v_lshlrev_b32_e32 v136, 16, v139
	v_and_b32_e32 v137, 0xffff0000, v139
	v_lshlrev_b32_e32 v138, 16, v140
	v_and_b32_e32 v139, 0xffff0000, v140
	v_lshlrev_b32_e32 v140, 16, v141
	v_and_b32_e32 v141, 0xffff0000, v141
	v_pk_mul_f32 v[136:137], v[118:119], v[136:137]
	v_pk_mul_f32 v[134:135], v[116:117], v[134:135]
	v_pk_mul_f32 v[140:141], v[114:115], v[140:141]
	v_pk_mul_f32 v[138:139], v[112:113], v[138:139]
	v_cvt_pk_bf16_f32 v134, v134, v135
	v_cvt_pk_bf16_f32 v135, v136, v137
	v_addc_co_u32_e32 v143, vcc, 0, v131, vcc
	v_cvt_pk_bf16_f32 v136, v138, v139
	v_cvt_pk_bf16_f32 v137, v140, v141
	v_add_co_u32_e32 v144, vcc, s42, v132
	global_store_dwordx4 v[142:143], v[134:137], off
	s_nop 0
	v_addc_co_u32_e32 v145, vcc, 0, v133, vcc
	s_waitcnt vmcnt(15)
	v_mov_b32_e32 v138, v210
	v_mov_b32_e32 v139, v211
	v_mov_b32_e32 v140, v212
	v_mov_b32_e32 v141, v213
	v_lshlrev_b32_e32 v134, 16, v138
	v_and_b32_e32 v135, 0xffff0000, v138
	v_lshlrev_b32_e32 v136, 16, v139
	v_and_b32_e32 v137, 0xffff0000, v139
	v_lshlrev_b32_e32 v138, 16, v140
	v_and_b32_e32 v139, 0xffff0000, v140
	v_lshlrev_b32_e32 v140, 16, v141
	v_and_b32_e32 v141, 0xffff0000, v141
	v_pk_mul_f32 v[136:137], v[86:87], v[136:137]
	v_pk_mul_f32 v[134:135], v[84:85], v[134:135]
	v_pk_mul_f32 v[140:141], v[82:83], v[140:141]
	v_pk_mul_f32 v[138:139], v[80:81], v[138:139]
	v_cvt_pk_bf16_f32 v134, v134, v135
	v_cvt_pk_bf16_f32 v135, v136, v137
	s_nop 0
	v_cvt_pk_bf16_f32 v136, v138, v139
	v_cvt_pk_bf16_f32 v137, v140, v141
	s_nop 0
	global_store_dwordx4 v[142:143], v[134:137], off offset:256
	v_add_co_u32_e32 v142, vcc, s42, v130
	s_waitcnt vmcnt(15)
; __device__ __forceinline__ float bf_lo(unsigned w) { return __uint_as_float(w << 16); }
; __device__ __forceinline__ float bf_hi(unsigned w) { return __uint_as_float(w & 0xffff0000u); }
; __device__ __forceinline__ u32x4 pack8(f32x4 v0, f32x4 v1) { u32x4 w; w.x = cvt_pk_bf16(v0[0], v0[1]); w.y = cvt_pk_bf16(v0[2], v0[3]); w.z = cvt_pk_bf16(v1[0], v1[1]); w.w = cvt_pk_bf16(v1[2], v1[3]); return w; }
;     __device__ __forceinline__ void operator()(const Acc& acc, const Unit& u, int wr, int wc, int fr, int fq) const {
;     ...
;         for (int ai = 0; ai < 2; ++ai)
; #pragma unroll
;             for (int m = 0; m < 4; ++m)
; #pragma unroll
;                 for (int bj = 0; bj < 2; ++bj) { const size_t o = o0 + (size_t)(ai * 128 + m * 16) * DM + bj * 128; const u32x4 w = __builtin_nontemporal_load((const u32x4*)(S2 + o));
;                     const f32x4 v0 = acc[ai][bj][m][0] * (f32x4){bf_lo(w.x), bf_hi(w.x), bf_lo(w.y), bf_hi(w.y)}, v1 = acc[ai][bj][m][1] * (f32x4){bf_lo(w.z), bf_hi(w.z), bf_lo(w.w), bf_hi(w.w)};
;                     *(u32x4*)(MG + o) = pack8(v0, v1); }
	v_mov_b32_e32 v138, v214
	v_mov_b32_e32 v139, v215
	v_mov_b32_e32 v140, v216
	v_mov_b32_e32 v141, v217
	v_lshlrev_b32_e32 v134, 16, v138
	v_and_b32_e32 v135, 0xffff0000, v138
	v_lshlrev_b32_e32 v136, 16, v139
	v_and_b32_e32 v137, 0xffff0000, v139
	v_lshlrev_b32_e32 v138, 16, v140
	v_and_b32_e32 v139, 0xffff0000, v140
	v_lshlrev_b32_e32 v140, 16, v141
	v_and_b32_e32 v141, 0xffff0000, v141
	v_pk_mul_f32 v[136:137], v[110:111], v[136:137]
	v_pk_mul_f32 v[134:135], v[108:109], v[134:135]
	v_pk_mul_f32 v[140:141], v[106:107], v[140:141]
	v_pk_mul_f32 v[138:139], v[104:105], v[138:139]
	v_cvt_pk_bf16_f32 v134, v134, v135
	v_cvt_pk_bf16_f32 v135, v136, v137
	v_addc_co_u32_e32 v143, vcc, 0, v131, vcc
	v_cvt_pk_bf16_f32 v136, v138, v139
	v_cvt_pk_bf16_f32 v137, v140, v141
	v_add_co_u32_e32 v144, vcc, s43, v132
	global_store_dwordx4 v[142:143], v[134:137], off
	s_nop 0
	v_addc_co_u32_e32 v145, vcc, 0, v133, vcc
	s_waitcnt vmcnt(15)
	v_mov_b32_e32 v138, v218
	v_mov_b32_e32 v139, v219
	v_mov_b32_e32 v140, v220
	v_mov_b32_e32 v141, v221
	v_lshlrev_b32_e32 v134, 16, v138
	v_and_b32_e32 v135, 0xffff0000, v138
	v_lshlrev_b32_e32 v136, 16, v139
	v_and_b32_e32 v137, 0xffff0000, v139
	v_lshlrev_b32_e32 v138, 16, v140
	v_and_b32_e32 v139, 0xffff0000, v140
	v_lshlrev_b32_e32 v140, 16, v141
	v_and_b32_e32 v141, 0xffff0000, v141
	v_pk_mul_f32 v[136:137], v[78:79], v[136:137]
	v_pk_mul_f32 v[134:135], v[76:77], v[134:135]
	v_pk_mul_f32 v[140:141], v[74:75], v[140:141]
	v_pk_mul_f32 v[138:139], v[72:73], v[138:139]
	v_cvt_pk_bf16_f32 v134, v134, v135
	v_cvt_pk_bf16_f32 v135, v136, v137
	s_nop 0
	v_cvt_pk_bf16_f32 v136, v138, v139
	v_cvt_pk_bf16_f32 v137, v140, v141
	s_nop 0
	global_store_dwordx4 v[142:143], v[134:137], off offset:256
	v_add_co_u32_e32 v142, vcc, s43, v130
	s_waitcnt vmcnt(15)
	v_mov_b32_e32 v138, v222
	v_mov_b32_e32 v139, v223
	v_mov_b32_e32 v140, v224
	v_mov_b32_e32 v141, v225
	v_lshlrev_b32_e32 v134, 16, v138
	v_and_b32_e32 v135, 0xffff0000, v138
	v_lshlrev_b32_e32 v136, 16, v139
	v_and_b32_e32 v137, 0xffff0000, v139
	v_lshlrev_b32_e32 v138, 16, v140
	v_and_b32_e32 v139, 0xffff0000, v140
	v_lshlrev_b32_e32 v140, 16, v141
	v_and_b32_e32 v141, 0xffff0000, v141
	v_pk_mul_f32 v[136:137], v[102:103], v[136:137]
	v_pk_mul_f32 v[134:135], v[100:101], v[134:135]
	v_pk_mul_f32 v[140:141], v[98:99], v[140:141]
	v_pk_mul_f32 v[138:139], v[96:97], v[138:139]
	v_cvt_pk_bf16_f32 v134, v134, v135
	v_cvt_pk_bf16_f32 v135, v136, v137
	v_addc_co_u32_e32 v143, vcc, 0, v131, vcc
	v_cvt_pk_bf16_f32 v136, v138, v139
	v_cvt_pk_bf16_f32 v137, v140, v141
	v_add_co_u32_e32 v144, vcc, s44, v132
	global_store_dwordx4 v[142:143], v[134:137], off
	s_nop 0
	v_addc_co_u32_e32 v145, vcc, 0, v133, vcc
	s_waitcnt vmcnt(15)
	v_mov_b32_e32 v138, v226
	v_mov_b32_e32 v139, v227
	v_mov_b32_e32 v140, v228
	v_mov_b32_e32 v141, v229
	v_lshlrev_b32_e32 v134, 16, v138
	v_and_b32_e32 v135, 0xffff0000, v138
	v_lshlrev_b32_e32 v136, 16, v139
	v_and_b32_e32 v137, 0xffff0000, v139
	v_lshlrev_b32_e32 v138, 16, v140
	v_and_b32_e32 v139, 0xffff0000, v140
	v_lshlrev_b32_e32 v140, 16, v141
	v_and_b32_e32 v141, 0xffff0000, v141
	v_pk_mul_f32 v[136:137], v[70:71], v[136:137]
	v_pk_mul_f32 v[134:135], v[68:69], v[134:135]
	v_pk_mul_f32 v[140:141], v[66:67], v[140:141]
	v_pk_mul_f32 v[138:139], v[64:65], v[138:139]
	v_cvt_pk_bf16_f32 v134, v134, v135
	v_cvt_pk_bf16_f32 v135, v136, v137
	s_nop 0
	v_cvt_pk_bf16_f32 v136, v138, v139
	v_cvt_pk_bf16_f32 v137, v140, v141
	s_nop 0
	global_store_dwordx4 v[142:143], v[134:137], off offset:256
	v_add_co_u32_e32 v142, vcc, s44, v130
	s_waitcnt vmcnt(15)
	v_mov_b32_e32 v138, v230
	v_mov_b32_e32 v139, v231
	v_mov_b32_e32 v140, v232
	v_mov_b32_e32 v141, v233
	v_lshlrev_b32_e32 v134, 16, v138
	v_and_b32_e32 v135, 0xffff0000, v138
	v_lshlrev_b32_e32 v136, 16, v139
	v_and_b32_e32 v137, 0xffff0000, v139
	v_lshlrev_b32_e32 v138, 16, v140
	v_and_b32_e32 v139, 0xffff0000, v140
	v_lshlrev_b32_e32 v140, 16, v141
	v_and_b32_e32 v141, 0xffff0000, v141
	v_pk_mul_f32 v[136:137], v[62:63], v[136:137]
	v_pk_mul_f32 v[134:135], v[60:61], v[134:135]
	v_pk_mul_f32 v[140:141], v[58:59], v[140:141]
	v_pk_mul_f32 v[138:139], v[56:57], v[138:139]
	v_cvt_pk_bf16_f32 v134, v134, v135
	v_cvt_pk_bf16_f32 v135, v136, v137
	v_addc_co_u32_e32 v143, vcc, 0, v131, vcc
	v_cvt_pk_bf16_f32 v136, v138, v139
	v_cvt_pk_bf16_f32 v137, v140, v141
	v_add_co_u32_e32 v144, vcc, s45, v132
	global_store_dwordx4 v[142:143], v[134:137], off
	s_nop 0
	v_addc_co_u32_e32 v145, vcc, 0, v133, vcc
	s_waitcnt vmcnt(15)
	v_mov_b32_e32 v138, v234
	v_mov_b32_e32 v139, v235
	v_mov_b32_e32 v140, v236
	v_mov_b32_e32 v141, v237
	v_lshlrev_b32_e32 v134, 16, v138
	v_and_b32_e32 v135, 0xffff0000, v138
	v_lshlrev_b32_e32 v136, 16, v139
	v_and_b32_e32 v137, 0xffff0000, v139
	v_lshlrev_b32_e32 v138, 16, v140
	v_and_b32_e32 v139, 0xffff0000, v140
	v_lshlrev_b32_e32 v140, 16, v141
	v_and_b32_e32 v141, 0xffff0000, v141
	v_pk_mul_f32 v[136:137], v[30:31], v[136:137]
	v_pk_mul_f32 v[134:135], v[28:29], v[134:135]
	v_pk_mul_f32 v[140:141], v[26:27], v[140:141]
	v_pk_mul_f32 v[138:139], v[24:25], v[138:139]
	v_cvt_pk_bf16_f32 v134, v134, v135
	v_cvt_pk_bf16_f32 v135, v136, v137
	s_nop 0
	v_cvt_pk_bf16_f32 v136, v138, v139
	v_cvt_pk_bf16_f32 v137, v140, v141
	s_nop 0
	global_store_dwordx4 v[142:143], v[134:137], off offset:256
	v_add_co_u32_e32 v142, vcc, s45, v130
	s_waitcnt vmcnt(15)
; __device__ __forceinline__ float bf_lo(unsigned w) { return __uint_as_float(w << 16); }
; __device__ __forceinline__ float bf_hi(unsigned w) { return __uint_as_float(w & 0xffff0000u); }
; __device__ __forceinline__ u32x4 pack8(f32x4 v0, f32x4 v1) { u32x4 w; w.x = cvt_pk_bf16(v0[0], v0[1]); w.y = cvt_pk_bf16(v0[2], v0[3]); w.z = cvt_pk_bf16(v1[0], v1[1]); w.w = cvt_pk_bf16(v1[2], v1[3]); return w; }
;     __device__ __forceinline__ void operator()(const Acc& acc, const Unit& u, int wr, int wc, int fr, int fq) const {
;     ...
;         for (int ai = 0; ai < 2; ++ai)
; #pragma unroll
;             for (int m = 0; m < 4; ++m)
; #pragma unroll
;                 for (int bj = 0; bj < 2; ++bj) { const size_t o = o0 + (size_t)(ai * 128 + m * 16) * DM + bj * 128; const u32x4 w = __builtin_nontemporal_load((const u32x4*)(S2 + o));
;                     const f32x4 v0 = acc[ai][bj][m][0] * (f32x4){bf_lo(w.x), bf_hi(w.x), bf_lo(w.y), bf_hi(w.y)}, v1 = acc[ai][bj][m][1] * (f32x4){bf_lo(w.z), bf_hi(w.z), bf_lo(w.w), bf_hi(w.w)};
;                     *(u32x4*)(MG + o) = pack8(v0, v1); }
	v_mov_b32_e32 v138, v238
	v_mov_b32_e32 v139, v239
	v_mov_b32_e32 v140, v240
	v_mov_b32_e32 v141, v241
	v_lshlrev_b32_e32 v134, 16, v138
	v_and_b32_e32 v135, 0xffff0000, v138
	v_lshlrev_b32_e32 v136, 16, v139
	v_and_b32_e32 v137, 0xffff0000, v139
	v_lshlrev_b32_e32 v138, 16, v140
	v_and_b32_e32 v139, 0xffff0000, v140
	v_lshlrev_b32_e32 v140, 16, v141
	v_and_b32_e32 v141, 0xffff0000, v141
	v_pk_mul_f32 v[136:137], v[54:55], v[136:137]
	v_pk_mul_f32 v[134:135], v[52:53], v[134:135]
	v_pk_mul_f32 v[140:141], v[50:51], v[140:141]
	v_pk_mul_f32 v[138:139], v[48:49], v[138:139]
	v_cvt_pk_bf16_f32 v134, v134, v135
	v_cvt_pk_bf16_f32 v135, v136, v137
	v_addc_co_u32_e32 v143, vcc, 0, v131, vcc
	v_cvt_pk_bf16_f32 v136, v138, v139
	v_cvt_pk_bf16_f32 v137, v140, v141
	v_add_co_u32_e32 v144, vcc, s46, v132
	global_store_dwordx4 v[142:143], v[134:137], off
	s_nop 0
	v_addc_co_u32_e32 v145, vcc, 0, v133, vcc
	s_waitcnt vmcnt(15)
	v_mov_b32_e32 v138, v242
	v_mov_b32_e32 v139, v243
	v_mov_b32_e32 v140, v244
	v_mov_b32_e32 v141, v245
	v_lshlrev_b32_e32 v134, 16, v138
	v_and_b32_e32 v135, 0xffff0000, v138
	v_lshlrev_b32_e32 v136, 16, v139
	v_and_b32_e32 v137, 0xffff0000, v139
	v_lshlrev_b32_e32 v138, 16, v140
	v_and_b32_e32 v139, 0xffff0000, v140
	v_lshlrev_b32_e32 v140, 16, v141
	v_and_b32_e32 v141, 0xffff0000, v141
	v_pk_mul_f32 v[136:137], v[22:23], v[136:137]
	v_pk_mul_f32 v[134:135], v[20:21], v[134:135]
	v_pk_mul_f32 v[140:141], v[18:19], v[140:141]
	v_pk_mul_f32 v[138:139], v[16:17], v[138:139]
	v_cvt_pk_bf16_f32 v134, v134, v135
	v_cvt_pk_bf16_f32 v135, v136, v137
	s_nop 0
	v_cvt_pk_bf16_f32 v136, v138, v139
	v_cvt_pk_bf16_f32 v137, v140, v141
	s_nop 0
	global_store_dwordx4 v[142:143], v[134:137], off offset:256
	v_add_co_u32_e32 v142, vcc, s46, v130
	s_waitcnt vmcnt(15)
	v_mov_b32_e32 v138, v164
	v_mov_b32_e32 v139, v165
	v_mov_b32_e32 v140, v166
	v_mov_b32_e32 v141, v167
	v_lshlrev_b32_e32 v134, 16, v138
	v_and_b32_e32 v135, 0xffff0000, v138
	v_lshlrev_b32_e32 v136, 16, v139
	v_and_b32_e32 v137, 0xffff0000, v139
	v_lshlrev_b32_e32 v138, 16, v140
	v_and_b32_e32 v139, 0xffff0000, v140
	v_lshlrev_b32_e32 v140, 16, v141
	v_and_b32_e32 v141, 0xffff0000, v141
	v_pk_mul_f32 v[136:137], v[46:47], v[136:137]
	v_pk_mul_f32 v[134:135], v[44:45], v[134:135]
	v_pk_mul_f32 v[140:141], v[42:43], v[140:141]
	v_pk_mul_f32 v[138:139], v[40:41], v[138:139]
	v_cvt_pk_bf16_f32 v134, v134, v135
	v_cvt_pk_bf16_f32 v135, v136, v137
	v_addc_co_u32_e32 v143, vcc, 0, v131, vcc
	v_cvt_pk_bf16_f32 v136, v138, v139
	v_cvt_pk_bf16_f32 v137, v140, v141
	v_add_co_u32_e32 v144, vcc, s47, v132
	global_store_dwordx4 v[142:143], v[134:137], off
	s_nop 0
	v_addc_co_u32_e32 v145, vcc, 0, v133, vcc
	s_waitcnt vmcnt(15)
	v_mov_b32_e32 v138, v168
	v_mov_b32_e32 v139, v169
	v_mov_b32_e32 v140, v170
	v_mov_b32_e32 v141, v171
	v_lshlrev_b32_e32 v132, 16, v138
	v_and_b32_e32 v133, 0xffff0000, v138
	v_lshlrev_b32_e32 v134, 16, v139
	v_and_b32_e32 v135, 0xffff0000, v139
	v_lshlrev_b32_e32 v136, 16, v140
	v_and_b32_e32 v137, 0xffff0000, v140
	v_lshlrev_b32_e32 v138, 16, v141
	v_and_b32_e32 v139, 0xffff0000, v141
	v_pk_mul_f32 v[134:135], v[14:15], v[134:135]
	v_pk_mul_f32 v[132:133], v[12:13], v[132:133]
	v_pk_mul_f32 v[138:139], v[10:11], v[138:139]
	v_pk_mul_f32 v[136:137], v[8:9], v[136:137]
	v_cvt_pk_bf16_f32 v132, v132, v133
	v_cvt_pk_bf16_f32 v133, v134, v135
	v_add_co_u32_e32 v140, vcc, s47, v130
	v_cvt_pk_bf16_f32 v134, v136, v137
	v_cvt_pk_bf16_f32 v135, v138, v139
	s_nop 0
	v_addc_co_u32_e32 v141, vcc, 0, v131, vcc
	global_store_dwordx4 v[142:143], v[132:135], off offset:256
	s_waitcnt vmcnt(15)
	v_mov_b32_e32 v136, v176
	v_mov_b32_e32 v137, v177
	v_mov_b32_e32 v138, v178
	v_mov_b32_e32 v139, v179
	s_nop 0
	v_lshlrev_b32_e32 v132, 16, v136
	v_and_b32_e32 v133, 0xffff0000, v136
	v_lshlrev_b32_e32 v134, 16, v137
	v_and_b32_e32 v135, 0xffff0000, v137
	v_lshlrev_b32_e32 v136, 16, v138
	v_and_b32_e32 v137, 0xffff0000, v138
	v_lshlrev_b32_e32 v138, 16, v139
	v_and_b32_e32 v139, 0xffff0000, v139
	v_pk_mul_f32 v[134:135], v[38:39], v[134:135]
	v_pk_mul_f32 v[132:133], v[36:37], v[132:133]
	v_pk_mul_f32 v[138:139], v[34:35], v[138:139]
	v_pk_mul_f32 v[136:137], v[32:33], v[136:137]
	v_cvt_pk_bf16_f32 v132, v132, v133
	v_cvt_pk_bf16_f32 v133, v134, v135
	s_nop 0
	v_cvt_pk_bf16_f32 v134, v136, v137
	v_cvt_pk_bf16_f32 v135, v138, v139
	s_waitcnt vmcnt(15)
	v_mov_b32_e32 v136, v180
	v_mov_b32_e32 v137, v181
	v_mov_b32_e32 v138, v182
	v_mov_b32_e32 v139, v183
	v_lshlrev_b32_e32 v130, 16, v136
	global_store_dwordx4 v[140:141], v[132:135], off
	v_and_b32_e32 v131, 0xffff0000, v136
	v_lshlrev_b32_e32 v136, 16, v139
	v_lshlrev_b32_e32 v132, 16, v137
	v_and_b32_e32 v133, 0xffff0000, v137
	v_lshlrev_b32_e32 v134, 16, v138
	v_and_b32_e32 v135, 0xffff0000, v138
	v_and_b32_e32 v137, 0xffff0000, v139
	v_pk_mul_f32 v[132:133], v[6:7], v[132:133]
	v_pk_mul_f32 v[130:131], v[4:5], v[130:131]
	v_pk_mul_f32 v[136:137], v[2:3], v[136:137]
	v_pk_mul_f32 v[134:135], v[0:1], v[134:135]
	v_cvt_pk_bf16_f32 v130, v130, v131
	v_cvt_pk_bf16_f32 v131, v132, v133
	s_nop 0
	v_cvt_pk_bf16_f32 v132, v134, v135
	v_cvt_pk_bf16_f32 v133, v136, v137
	global_store_dwordx4 v[140:141], v[130:133], off offset:256
	s_cbranch_execnz .LBB0_671
